# NSA top-16 block selection: serial per-block rank loop replaced by a ballot radix select of the 16th largest key (same mask); P11 epilogue x2/pe operands prefetched 8 sub-blocks ahead
# speedup vs baseline: 1.0219x; 1.0219x over previous
; __device__ __forceinline__ void nsa_phase(LAS unsigned char* lds, const Args& a, const bf16_t* z, const bf16_t* KC, const bf16_t* VCT, const bf16_t* VST, const bf16_t* VWT, bf16_t* A2, int ldo, bool merged) {
;     ...
;         for (int qi = 0; qi < 8; ++qi) {
;             const int q = wid * 8 + qi, j = lane;
;             const float imp = ((IMP[(0 * 64 + q) * 65 + j] + IMP[(1 * 64 + q) * 65 + j]) + IMP[(2 * 64 + q) * 65 + j]) + IMP[(3 * 64 + q) * 65 + j];
;             const bool forced = (j == 0) || (j == cur) || (j == cur - 1);
;             const bool valid = (j <= cur);
;             unsigned key = forced ? 0xFFFFFFC0u : (valid ? (__float_as_uint(fmaxf(imp, 0.f)) & 0xFFFFFFC0u) : 0u);
;             key |= (unsigned)(63 - j);
;             int rank = 0;
; #pragma unroll 8
;             for (int jp = 0; jp <= cur; ++jp) { const unsigned kj = (unsigned)__builtin_amdgcn_readlane((int)key, jp); rank += (kj > key) ? 1 : 0; }
;             const unsigned long long mk = __ballot((rank < 16) && valid);
;             if (lane == 0) { SELM[2 * q] = (unsigned)mk; SELM[2 * q + 1] = (unsigned)(mk >> 32); atomicOr((unsigned*)&UNI[0], (unsigned)mk); atomicOr((unsigned*)&UNI[1], (unsigned)(mk >> 32)); }
;         }
.LBB0_1038:
	s_barrier
	v_cmp_eq_u32_e32 vcc, s63, v158
	s_add_i32 s6, s63, -1
	s_or_b64 s[0:1], s[4:5], vcc
	v_cmp_eq_u32_e32 vcc, s6, v158
	s_or_b64 s[6:7], s[0:1], vcc
	v_cmp_ge_u32_e32 vcc, s63, v158
	s_mov_b64 s[14:15], vcc
	ds_read2st64_b32 v[60:61], v173 offset1:65
	ds_read2st64_b32 v[62:63], v173 offset0:130 offset1:195
	ds_read2st64_b32 v[64:65], v175 offset1:65
	ds_read2st64_b32 v[66:67], v175 offset0:130 offset1:195
	ds_read2st64_b32 v[68:69], v186 offset1:65
	ds_read2st64_b32 v[70:71], v186 offset0:130 offset1:195
	ds_read2st64_b32 v[72:73], v187 offset1:65
	ds_read2st64_b32 v[74:75], v187 offset0:130 offset1:195
	ds_read2st64_b32 v[76:77], v188 offset1:65
	ds_read2st64_b32 v[78:79], v188 offset0:130 offset1:195
	ds_read2st64_b32 v[80:81], v189 offset1:65
	ds_read2st64_b32 v[82:83], v189 offset0:130 offset1:195
	ds_read2st64_b32 v[84:85], v190 offset1:65
	ds_read2st64_b32 v[86:87], v190 offset0:130 offset1:195
	ds_read2st64_b32 v[88:89], v191 offset1:65
	ds_read2st64_b32 v[90:91], v191 offset0:130 offset1:195
	s_waitcnt lgkmcnt(14)
	v_add_f32_e32 v52, v60, v61
	v_add_f32_e32 v52, v52, v62
	v_add_f32_e32 v52, v52, v63
	v_max_f32_e32 v52, 0, v52
	v_and_b32_e32 v52, 0xffffffc0, v52
	v_cndmask_b32_e32 v52, 0, v52, vcc
	v_cndmask_b32_e64 v52, v52, v196, s[6:7]
	v_bitop3_b32 v52, v52, 63, v158 bitop3:0x36
	s_waitcnt lgkmcnt(12)
	v_add_f32_e32 v53, v64, v65
	v_add_f32_e32 v53, v53, v66
	v_add_f32_e32 v53, v53, v67
	v_max_f32_e32 v53, 0, v53
	v_and_b32_e32 v53, 0xffffffc0, v53
	v_cndmask_b32_e32 v53, 0, v53, vcc
	v_cndmask_b32_e64 v53, v53, v196, s[6:7]
	v_bitop3_b32 v53, v53, 63, v158 bitop3:0x36
	s_waitcnt lgkmcnt(10)
	v_add_f32_e32 v54, v68, v69
	v_add_f32_e32 v54, v54, v70
	v_add_f32_e32 v54, v54, v71
	v_max_f32_e32 v54, 0, v54
	v_and_b32_e32 v54, 0xffffffc0, v54
	v_cndmask_b32_e32 v54, 0, v54, vcc
	v_cndmask_b32_e64 v54, v54, v196, s[6:7]
	v_bitop3_b32 v54, v54, 63, v158 bitop3:0x36
	s_waitcnt lgkmcnt(8)
	v_add_f32_e32 v55, v72, v73
	v_add_f32_e32 v55, v55, v74
	v_add_f32_e32 v55, v55, v75
	v_max_f32_e32 v55, 0, v55
	v_and_b32_e32 v55, 0xffffffc0, v55
	v_cndmask_b32_e32 v55, 0, v55, vcc
	v_cndmask_b32_e64 v55, v55, v196, s[6:7]
	v_bitop3_b32 v55, v55, 63, v158 bitop3:0x36
	s_waitcnt lgkmcnt(6)
	v_add_f32_e32 v56, v76, v77
	v_add_f32_e32 v56, v56, v78
	v_add_f32_e32 v56, v56, v79
	v_max_f32_e32 v56, 0, v56
	v_and_b32_e32 v56, 0xffffffc0, v56
	v_cndmask_b32_e32 v56, 0, v56, vcc
	v_cndmask_b32_e64 v56, v56, v196, s[6:7]
	v_bitop3_b32 v56, v56, 63, v158 bitop3:0x36
	s_waitcnt lgkmcnt(4)
	v_add_f32_e32 v57, v80, v81
	v_add_f32_e32 v57, v57, v82
	v_add_f32_e32 v57, v57, v83
	v_max_f32_e32 v57, 0, v57
	v_and_b32_e32 v57, 0xffffffc0, v57
	v_cndmask_b32_e32 v57, 0, v57, vcc
	v_cndmask_b32_e64 v57, v57, v196, s[6:7]
	v_bitop3_b32 v57, v57, 63, v158 bitop3:0x36
	s_waitcnt lgkmcnt(2)
	v_add_f32_e32 v58, v84, v85
	v_add_f32_e32 v58, v58, v86
	v_add_f32_e32 v58, v58, v87
	v_max_f32_e32 v58, 0, v58
	v_and_b32_e32 v58, 0xffffffc0, v58
	v_cndmask_b32_e32 v58, 0, v58, vcc
	v_cndmask_b32_e64 v58, v58, v196, s[6:7]
	v_bitop3_b32 v58, v58, 63, v158 bitop3:0x36
	s_waitcnt lgkmcnt(0)
	v_add_f32_e32 v59, v88, v89
	v_add_f32_e32 v59, v59, v90
	v_add_f32_e32 v59, v59, v91
	v_max_f32_e32 v59, 0, v59
	v_and_b32_e32 v59, 0xffffffc0, v59
	v_cndmask_b32_e32 v59, 0, v59, vcc
	v_cndmask_b32_e64 v59, v59, v196, s[6:7]
	v_bitop3_b32 v59, v59, 63, v158 bitop3:0x36
	s_mov_b32 s28, 0
	s_mov_b32 s29, 0
	s_mov_b32 s32, 0
	s_mov_b32 s60, 0
	s_mov_b32 s69, 0
	s_mov_b32 s70, 0
	s_mov_b32 s74, 0
	s_mov_b32 s75, 0
	s_brev_b32 s77, 1
.Ltopk_bit:
	s_or_b32 s23, s28, s77
	s_or_b32 s24, s29, s77
	s_or_b32 s25, s32, s77
	s_or_b32 s27, s60, s77
	v_cmp_le_u32_e64 s[0:1], s23, v52
	v_cmp_le_u32_e64 s[8:9], s24, v53
	v_cmp_le_u32_e64 s[10:11], s25, v54
	v_cmp_le_u32_e64 s[12:13], s27, v55
	s_bcnt1_i32_b64 s79, s[0:1]
	s_cmp_gt_u32 s79, 15
	s_cselect_b32 s28, s23, s28
	s_bcnt1_i32_b64 s79, s[8:9]
	s_cmp_gt_u32 s79, 15
	s_cselect_b32 s29, s24, s29
	s_bcnt1_i32_b64 s79, s[10:11]
	s_cmp_gt_u32 s79, 15
	s_cselect_b32 s32, s25, s32
	s_bcnt1_i32_b64 s79, s[12:13]
	s_cmp_gt_u32 s79, 15
	s_cselect_b32 s60, s27, s60
	s_or_b32 s23, s69, s77
	s_or_b32 s24, s70, s77
	s_or_b32 s25, s74, s77
	s_or_b32 s27, s75, s77
	v_cmp_le_u32_e64 s[0:1], s23, v56
	v_cmp_le_u32_e64 s[8:9], s24, v57
	v_cmp_le_u32_e64 s[10:11], s25, v58
	v_cmp_le_u32_e64 s[12:13], s27, v59
	s_bcnt1_i32_b64 s79, s[0:1]
	s_cmp_gt_u32 s79, 15
	s_cselect_b32 s69, s23, s69
	s_bcnt1_i32_b64 s79, s[8:9]
	s_cmp_gt_u32 s79, 15
	s_cselect_b32 s70, s24, s70
	s_bcnt1_i32_b64 s79, s[10:11]
	s_cmp_gt_u32 s79, 15
	s_cselect_b32 s74, s25, s74
	s_bcnt1_i32_b64 s79, s[12:13]
	s_cmp_gt_u32 s79, 15
	s_cselect_b32 s75, s27, s75
	s_lshr_b32 s77, s77, 1
	s_cmp_lg_u32 s77, 0
	s_cbranch_scc1 .Ltopk_bit
	s_mov_b64 s[24:25], 0
	s_add_i32 s79, s71, 0x21800
	v_mov_b32_e32 v1, s79
	s_mov_b64 s[12:13], exec
	v_cmp_le_u32_e64 s[10:11], s28, v52
	s_and_b64 s[10:11], s[10:11], s[14:15]
	s_or_b64 s[24:25], s[24:25], s[10:11]
	v_mov_b32_e32 v2, s10
	v_mov_b32_e32 v3, s11
	s_mov_b64 exec, s[4:5]
	ds_write_b64 v1, v[2:3]
	s_mov_b64 exec, s[12:13]
	v_cmp_le_u32_e64 s[10:11], s29, v53
	s_and_b64 s[10:11], s[10:11], s[14:15]
	s_or_b64 s[24:25], s[24:25], s[10:11]
	v_mov_b32_e32 v2, s10
	v_mov_b32_e32 v3, s11
	s_mov_b64 exec, s[4:5]
	ds_write_b64 v1, v[2:3] offset:8
	s_mov_b64 exec, s[12:13]
	v_cmp_le_u32_e64 s[10:11], s32, v54
	s_and_b64 s[10:11], s[10:11], s[14:15]
	s_or_b64 s[24:25], s[24:25], s[10:11]
	v_mov_b32_e32 v2, s10
	v_mov_b32_e32 v3, s11
	s_mov_b64 exec, s[4:5]
	ds_write_b64 v1, v[2:3] offset:16
	s_mov_b64 exec, s[12:13]
	v_cmp_le_u32_e64 s[10:11], s60, v55
	s_and_b64 s[10:11], s[10:11], s[14:15]
	s_or_b64 s[24:25], s[24:25], s[10:11]
	v_mov_b32_e32 v2, s10
	v_mov_b32_e32 v3, s11
	s_mov_b64 exec, s[4:5]
	ds_write_b64 v1, v[2:3] offset:24
	s_mov_b64 exec, s[12:13]
	v_cmp_le_u32_e64 s[10:11], s69, v56
	s_and_b64 s[10:11], s[10:11], s[14:15]
	s_or_b64 s[24:25], s[24:25], s[10:11]
	v_mov_b32_e32 v2, s10
	v_mov_b32_e32 v3, s11
	s_mov_b64 exec, s[4:5]
	ds_write_b64 v1, v[2:3] offset:32
	s_mov_b64 exec, s[12:13]
	v_cmp_le_u32_e64 s[10:11], s70, v57
	s_and_b64 s[10:11], s[10:11], s[14:15]
	s_or_b64 s[24:25], s[24:25], s[10:11]
	v_mov_b32_e32 v2, s10
	v_mov_b32_e32 v3, s11
	s_mov_b64 exec, s[4:5]
	ds_write_b64 v1, v[2:3] offset:40
	s_mov_b64 exec, s[12:13]
	v_cmp_le_u32_e64 s[10:11], s74, v58
	s_and_b64 s[10:11], s[10:11], s[14:15]
	s_or_b64 s[24:25], s[24:25], s[10:11]
	v_mov_b32_e32 v2, s10
	v_mov_b32_e32 v3, s11
	s_mov_b64 exec, s[4:5]
	ds_write_b64 v1, v[2:3] offset:48
	s_mov_b64 exec, s[12:13]
	v_cmp_le_u32_e64 s[10:11], s75, v59
	s_and_b64 s[10:11], s[10:11], s[14:15]
	s_or_b64 s[24:25], s[24:25], s[10:11]
	v_mov_b32_e32 v2, s10
	v_mov_b32_e32 v3, s11
	s_mov_b64 exec, s[4:5]
	ds_write_b64 v1, v[2:3] offset:56
	s_mov_b64 exec, s[12:13]
	v_mov_b32_e32 v2, s24
	v_mov_b32_e32 v3, s25
	v_mov_b32_e32 v60, s82
	v_mov_b32_e32 v61, s93
	s_mov_b64 exec, s[4:5]
	ds_or_b32 v60, v2
	ds_or_b32 v61, v3
	s_mov_b64 exec, s[12:13]
	s_mov_b64 s[0:1], exec

; __device__ __forceinline__ float sigm(float x) { return __builtin_amdgcn_rcpf(1.f + __expf(-x)); }
;     __device__ __forceinline__ void operator()(const f32x4 (&acc)[2][2][4][2], const pg8::Unit& u, int wr, int wc, int fr, int fq) const {
;     ...
;                         float* op = outf + (size_t)r * DM + c0;
;                         const u32x4 xw = *(const u32x4*)(O + (size_t)r * DM + c0);
;                         float xf[8]; unpack8(xw, xf);
;                         const u32x4 pw = *(const u32x4*)(pe + (size_t)r * DM + c0);
;                         float pf[8]; unpack8(pw, pf);
;                         f32x4 o0, o1;
; #pragma unroll
;                         for (int j = 0; j < 4; ++j) { o0[j] = xf[j] + sigm(v[j]) * pf[j]; o1[j] = xf[4 + j] + sigm(v[4 + j]) * pf[4 + j]; }
;                         *(f32x4*)op = o0; *(f32x4*)(op + 4) = o1;
.LBB0_1912:
	v_lshl_add_u32 v146, s18, 8, v148
	v_lshl_or_b32 v162, s37, 8, v150
	v_ashrrev_i32_e32 v147, 31, v146
	v_ashrrev_i32_e32 v163, 31, v162
	v_lshlrev_b64 v[158:159], 11, v[146:147]
	v_lshl_add_u64 v[154:155], s[48:49], 0, v[158:159]
	v_lshlrev_b64 v[144:145], 1, v[162:163]
	v_lshl_add_u64 v[158:159], s[38:39], 0, v[158:159]
	v_lshl_add_u64 v[164:165], v[154:155], 0, v[144:145]
	v_lshl_add_u64 v[166:167], v[158:159], 0, v[144:145]
	s_mov_b64 s[60:61], 0x8000
	s_mov_b64 s[62:63], 0x28000
	v_mov_b64_e32 v[244:245], v[164:165]
	v_mov_b64_e32 v[248:249], v[166:167]
	global_load_dwordx4 v[180:183], v[244:245], off
	global_load_dwordx4 v[184:187], v[248:249], off
	global_load_dwordx4 v[188:191], v[244:245], off offset:256
	global_load_dwordx4 v[192:195], v[248:249], off offset:256
	v_lshl_add_u64 v[244:245], v[244:245], 0, s[60:61]
	v_lshl_add_u64 v[248:249], v[248:249], 0, s[60:61]
	global_load_dwordx4 v[196:199], v[244:245], off
	global_load_dwordx4 v[200:203], v[248:249], off
	global_load_dwordx4 v[204:207], v[244:245], off offset:256
	global_load_dwordx4 v[208:211], v[248:249], off offset:256
	v_lshl_add_u64 v[244:245], v[244:245], 0, s[60:61]
	v_lshl_add_u64 v[248:249], v[248:249], 0, s[60:61]
	global_load_dwordx4 v[212:215], v[244:245], off
	global_load_dwordx4 v[216:219], v[248:249], off
	global_load_dwordx4 v[220:223], v[244:245], off offset:256
	global_load_dwordx4 v[224:227], v[248:249], off offset:256
	v_lshl_add_u64 v[244:245], v[244:245], 0, s[60:61]
	v_lshl_add_u64 v[248:249], v[248:249], 0, s[60:61]
	global_load_dwordx4 v[228:231], v[244:245], off
	global_load_dwordx4 v[232:235], v[248:249], off
	global_load_dwordx4 v[236:239], v[244:245], off offset:256
	global_load_dwordx4 v[240:243], v[248:249], off offset:256
	v_lshl_add_u64 v[244:245], v[244:245], 0, s[62:63]
	v_lshl_add_u64 v[248:249], v[248:249], 0, s[62:63]
	v_mul_f32_e32 v124, 0xbfb8aa3b, v124
	v_mul_f32_e32 v120, 0xbfb8aa3b, v120
	v_mul_f32_e32 v125, 0xbfb8aa3b, v125
	v_mul_f32_e32 v121, 0xbfb8aa3b, v121
	v_mul_f32_e32 v126, 0xbfb8aa3b, v126
	v_mul_f32_e32 v122, 0xbfb8aa3b, v122
	v_mul_f32_e32 v127, 0xbfb8aa3b, v127
	v_mul_f32_e32 v123, 0xbfb8aa3b, v123
	v_exp_f32_e32 v124, v124
	v_exp_f32_e32 v168, v120
	v_exp_f32_e32 v125, v125
	v_exp_f32_e32 v169, v121
	v_exp_f32_e32 v170, v126
	v_exp_f32_e32 v171, v122
	v_exp_f32_e32 v172, v127
	v_exp_f32_e32 v173, v123
	v_lshlrev_b64 v[122:123], 12, v[146:147]
	v_lshlrev_b64 v[120:121], 2, v[162:163]
	v_lshl_add_u64 v[122:123], s[84:85], 0, v[122:123]
	v_lshl_add_u64 v[126:127], v[122:123], 0, v[120:121]
	v_add_f32_e32 v122, 1.0, v124
	v_add_f32_e32 v123, 1.0, v168
	v_add_f32_e32 v125, 1.0, v125
	v_add_f32_e32 v147, 1.0, v169
	v_add_f32_e32 v162, 1.0, v170
	v_add_f32_e32 v163, 1.0, v171
	v_add_f32_e32 v169, 1.0, v172
	v_add_f32_e32 v170, 1.0, v173
	v_rcp_f32_e32 v122, v122
	v_rcp_f32_e32 v124, v123
	v_rcp_f32_e32 v123, v125
	v_rcp_f32_e32 v125, v147
	v_rcp_f32_e32 v162, v162
	v_rcp_f32_e32 v168, v163
	v_rcp_f32_e32 v163, v169
	v_rcp_f32_e32 v169, v170
	v_mul_f32_e32 v116, 0xbfb8aa3b, v116
	v_mul_f32_e32 v112, 0xbfb8aa3b, v112
	v_mul_f32_e32 v117, 0xbfb8aa3b, v117
	v_mul_f32_e32 v113, 0xbfb8aa3b, v113
	v_mul_f32_e32 v118, 0xbfb8aa3b, v118
	v_mul_f32_e32 v119, 0xbfb8aa3b, v119
	v_mul_f32_e32 v114, 0xbfb8aa3b, v114
	v_mul_f32_e32 v115, 0xbfb8aa3b, v115
	v_exp_f32_e32 v116, v116
	v_exp_f32_e32 v147, v112
	v_exp_f32_e32 v117, v117
	v_exp_f32_e32 v118, v118
	v_exp_f32_e32 v119, v119
	v_mul_f32_e32 v108, 0xbfb8aa3b, v108
	v_mul_f32_e32 v104, 0xbfb8aa3b, v104
	v_add_f32_e32 v118, 1.0, v118
	v_add_f32_e32 v119, 1.0, v119
	v_rcp_f32_e32 v118, v118
	v_rcp_f32_e32 v119, v119
	v_mul_f32_e32 v109, 0xbfb8aa3b, v109
	v_mul_f32_e32 v105, 0xbfb8aa3b, v105
	v_mul_f32_e32 v110, 0xbfb8aa3b, v110
	v_mul_f32_e32 v111, 0xbfb8aa3b, v111
	v_mul_f32_e32 v106, 0xbfb8aa3b, v106
	v_mul_f32_e32 v107, 0xbfb8aa3b, v107
	v_exp_f32_e32 v108, v108
	v_exp_f32_e32 v109, v109
	v_exp_f32_e32 v110, v110
	v_exp_f32_e32 v111, v111
	v_exp_f32_e32 v106, v106
	v_exp_f32_e32 v107, v107
	v_add_f32_e32 v108, 1.0, v108
	v_add_f32_e32 v109, 1.0, v109
	v_add_f32_e32 v110, 1.0, v110
	v_add_f32_e32 v111, 1.0, v111
	v_rcp_f32_e32 v110, v110
	v_rcp_f32_e32 v111, v111
	v_mul_f32_e32 v100, 0xbfb8aa3b, v100
	v_mul_f32_e32 v96, 0xbfb8aa3b, v96
	v_mul_f32_e32 v101, 0xbfb8aa3b, v101
	v_mul_f32_e32 v97, 0xbfb8aa3b, v97
	v_mul_f32_e32 v102, 0xbfb8aa3b, v102
	s_waitcnt vmcnt(14)
; __device__ __forceinline__ float sigm(float x) { return __builtin_amdgcn_rcpf(1.f + __expf(-x)); }
;     __device__ __forceinline__ void operator()(const f32x4 (&acc)[2][2][4][2], const pg8::Unit& u, int wr, int wc, int fr, int fq) const {
;     ...
;                         float* op = outf + (size_t)r * DM + c0;
;                         const u32x4 xw = *(const u32x4*)(O + (size_t)r * DM + c0);
;                         float xf[8]; unpack8(xw, xf);
;                         const u32x4 pw = *(const u32x4*)(pe + (size_t)r * DM + c0);
;                         float pf[8]; unpack8(pw, pf);
;                         f32x4 o0, o1;
; #pragma unroll
;                         for (int j = 0; j < 4; ++j) { o0[j] = xf[j] + sigm(v[j]) * pf[j]; o1[j] = xf[4 + j] + sigm(v[4 + j]) * pf[4 + j]; }
;                         *(f32x4*)op = o0; *(f32x4*)(op + 4) = o1;
	v_mov_b64_e32 v[154:155], v[180:181]
	v_mov_b64_e32 v[156:157], v[182:183]
	v_mov_b64_e32 v[158:159], v[184:185]
	v_mov_b64_e32 v[160:161], v[186:187]
	v_lshlrev_b32_e32 v170, 16, v154
	v_and_b32_e32 v171, 0xffff0000, v154
	v_lshlrev_b32_e32 v172, 16, v158
	v_and_b32_e32 v173, 0xffff0000, v158
	v_lshlrev_b32_e32 v174, 16, v156
	v_and_b32_e32 v175, 0xffff0000, v156
	v_lshlrev_b32_e32 v176, 16, v160
	v_and_b32_e32 v177, 0xffff0000, v160
	v_lshlrev_b32_e32 v178, 16, v155
	v_and_b32_e32 v179, 0xffff0000, v155
	v_lshlrev_b32_e32 v158, 16, v159
	v_and_b32_e32 v159, 0xffff0000, v159
	v_lshlrev_b32_e32 v156, 16, v157
	v_and_b32_e32 v157, 0xffff0000, v157
	v_lshlrev_b32_e32 v160, 16, v161
	v_and_b32_e32 v161, 0xffff0000, v161
	v_pk_fma_f32 v[122:123], v[122:123], v[172:173], v[170:171]
	v_pk_fma_f32 v[154:155], v[124:125], v[176:177], v[174:175]
	v_pk_fma_f32 v[124:125], v[162:163], v[158:159], v[178:179]
	v_pk_fma_f32 v[156:157], v[168:169], v[160:161], v[156:157]
	global_store_dwordx4 v[126:127], v[122:125], off
	global_store_dwordx4 v[126:127], v[154:157], off offset:16
	global_load_dwordx4 v[180:183], v[244:245], off
	global_load_dwordx4 v[184:187], v[248:249], off
	v_exp_f32_e32 v162, v113
	v_exp_f32_e32 v163, v114
	v_exp_f32_e32 v164, v115
	v_or_b32_e32 v158, 16, v146
	v_ashrrev_i32_e32 v159, 31, v158
	v_lshlrev_b64 v[112:113], 11, v[158:159]
	v_lshl_add_u64 v[114:115], s[48:49], 0, v[112:113]
	v_lshl_add_u64 v[160:161], s[38:39], 0, v[112:113]
	v_add_f32_e32 v112, 1.0, v116
	v_add_f32_e32 v113, 1.0, v147
	v_add_f32_e32 v116, 1.0, v117
	v_add_f32_e32 v117, 1.0, v162
	v_add_f32_e32 v147, 1.0, v163
	v_add_f32_e32 v165, 1.0, v164
	v_lshl_add_u64 v[162:163], v[114:115], 0, v[144:145]
	v_rcp_f32_e32 v112, v112
	v_rcp_f32_e32 v114, v113
	v_rcp_f32_e32 v113, v116
	v_rcp_f32_e32 v115, v117
	v_rcp_f32_e32 v164, v147
	v_rcp_f32_e32 v165, v165
	v_add_f32_e32 v147, 1.0, v106
	v_mul_f32_e32 v103, 0xbfb8aa3b, v103
	v_mul_f32_e32 v98, 0xbfb8aa3b, v98
	v_mul_f32_e32 v99, 0xbfb8aa3b, v99
	v_exp_f32_e32 v100, v100
	v_exp_f32_e32 v101, v101
	v_exp_f32_e32 v102, v102
	v_exp_f32_e32 v103, v103
	v_mul_f32_e32 v92, 0xbfb8aa3b, v92
	v_mul_f32_e32 v88, 0xbfb8aa3b, v88
	v_add_f32_e32 v102, 1.0, v102
	v_add_f32_e32 v103, 1.0, v103
	v_rcp_f32_e32 v102, v102
	v_rcp_f32_e32 v103, v103
	v_mul_f32_e32 v93, 0xbfb8aa3b, v93
	v_mul_f32_e32 v89, 0xbfb8aa3b, v89
	v_mul_f32_e32 v94, 0xbfb8aa3b, v94
	v_mul_f32_e32 v95, 0xbfb8aa3b, v95
	v_mul_f32_e32 v90, 0xbfb8aa3b, v90
	v_mul_f32_e32 v91, 0xbfb8aa3b, v91
	v_exp_f32_e32 v92, v92
	v_exp_f32_e32 v93, v93
	v_exp_f32_e32 v94, v94
	v_exp_f32_e32 v95, v95
	v_exp_f32_e32 v90, v90
	v_exp_f32_e32 v91, v91
	v_add_f32_e32 v92, 1.0, v92
	v_add_f32_e32 v93, 1.0, v93
	v_add_f32_e32 v94, 1.0, v94
	v_add_f32_e32 v95, 1.0, v95
	v_rcp_f32_e32 v94, v94
	v_rcp_f32_e32 v95, v95
	v_mul_f32_e32 v84, 0xbfb8aa3b, v84
	v_mul_f32_e32 v80, 0xbfb8aa3b, v80
	v_mul_f32_e32 v85, 0xbfb8aa3b, v85
	v_mul_f32_e32 v81, 0xbfb8aa3b, v81
	v_mul_f32_e32 v86, 0xbfb8aa3b, v86
	v_mul_f32_e32 v87, 0xbfb8aa3b, v87
	v_mul_f32_e32 v82, 0xbfb8aa3b, v82
	v_mul_f32_e32 v83, 0xbfb8aa3b, v83
	v_exp_f32_e32 v84, v84
	v_exp_f32_e32 v85, v85
	v_exp_f32_e32 v86, v86
	v_exp_f32_e32 v87, v87
	v_mul_f32_e32 v76, 0xbfb8aa3b, v76
	v_mul_f32_e32 v72, 0xbfb8aa3b, v72
	v_add_f32_e32 v86, 1.0, v86
	v_add_f32_e32 v87, 1.0, v87
	v_rcp_f32_e32 v86, v86
	v_rcp_f32_e32 v87, v87
	v_mul_f32_e32 v77, 0xbfb8aa3b, v77
	v_mul_f32_e32 v73, 0xbfb8aa3b, v73
	v_mul_f32_e32 v78, 0xbfb8aa3b, v78
	v_mul_f32_e32 v79, 0xbfb8aa3b, v79
	v_mul_f32_e32 v74, 0xbfb8aa3b, v74
	v_mul_f32_e32 v75, 0xbfb8aa3b, v75
	v_exp_f32_e32 v76, v76
	s_waitcnt vmcnt(16)
	v_mov_b64_e32 v[122:123], v[188:189]
	v_mov_b64_e32 v[124:125], v[190:191]
	v_mov_b64_e32 v[154:155], v[192:193]
	v_mov_b64_e32 v[156:157], v[194:195]
	v_lshlrev_b32_e32 v116, 16, v122
	v_and_b32_e32 v117, 0xffff0000, v122
	v_lshlrev_b32_e32 v166, 16, v154
	v_and_b32_e32 v167, 0xffff0000, v154
	v_lshlrev_b32_e32 v168, 16, v124
	v_and_b32_e32 v169, 0xffff0000, v124
	v_lshlrev_b32_e32 v170, 16, v156
	v_and_b32_e32 v171, 0xffff0000, v156
	v_lshlrev_b32_e32 v122, 16, v123
	v_and_b32_e32 v123, 0xffff0000, v123
	v_lshlrev_b32_e32 v154, 16, v155
	v_and_b32_e32 v155, 0xffff0000, v155
	v_lshlrev_b32_e32 v124, 16, v125
	v_and_b32_e32 v125, 0xffff0000, v125
	v_lshlrev_b32_e32 v156, 16, v157
	v_and_b32_e32 v157, 0xffff0000, v157
	v_pk_fma_f32 v[112:113], v[112:113], v[166:167], v[116:117]
	v_pk_fma_f32 v[116:117], v[114:115], v[170:171], v[168:169]
	v_pk_fma_f32 v[114:115], v[118:119], v[154:155], v[122:123]
	v_pk_fma_f32 v[118:119], v[164:165], v[156:157], v[124:125]
	global_store_dwordx4 v[126:127], v[112:115], off offset:512
	global_store_dwordx4 v[126:127], v[116:119], off offset:528
	global_load_dwordx4 v[188:191], v[244:245], off offset:256
	global_load_dwordx4 v[192:195], v[248:249], off offset:256
	v_lshl_add_u64 v[244:245], v[244:245], 0, s[60:61]
	v_lshl_add_u64 v[248:249], v[248:249], 0, s[60:61]
	v_lshl_add_u64 v[122:123], v[160:161], 0, v[144:145]
	v_exp_f32_e32 v124, v104
	v_exp_f32_e32 v125, v105
	v_lshlrev_b64 v[104:105], 12, v[158:159]
	v_lshl_add_u64 v[104:105], s[84:85], 0, v[104:105]
	v_add_f32_e32 v126, 1.0, v124
	v_add_f32_e32 v127, 1.0, v125
	v_add_f32_e32 v154, 1.0, v107
	v_lshl_add_u64 v[124:125], v[104:105], 0, v[120:121]
	v_rcp_f32_e32 v104, v108
	v_rcp_f32_e32 v106, v126
	v_rcp_f32_e32 v105, v109
	v_rcp_f32_e32 v107, v127
	v_rcp_f32_e32 v126, v147
	v_rcp_f32_e32 v127, v154
	v_exp_f32_e32 v77, v77
	v_exp_f32_e32 v78, v78
	v_exp_f32_e32 v79, v79
	v_exp_f32_e32 v74, v74
	v_exp_f32_e32 v75, v75
	v_add_f32_e32 v76, 1.0, v76
	v_add_f32_e32 v77, 1.0, v77
; __device__ __forceinline__ float bf_lo(unsigned w) { return __uint_as_float(w << 16); }
; __device__ __forceinline__ float bf_hi(unsigned w) { return __uint_as_float(w & 0xffff0000u); }
; __device__ __forceinline__ float sigm(float x) { return __builtin_amdgcn_rcpf(1.f + __expf(-x)); }
; __device__ __forceinline__ void unpack8(const u32x4 w, float (&f)[8]) {
;     f[0] = bf_lo(w.x); f[1] = bf_hi(w.x); f[2] = bf_lo(w.y); f[3] = bf_hi(w.y); f[4] = bf_lo(w.z); f[5] = bf_hi(w.z); f[6] = bf_lo(w.w); f[7] = bf_hi(w.w); }
;     __device__ __forceinline__ void operator()(const f32x4 (&acc)[2][2][4][2], const pg8::Unit& u, int wr, int wc, int fr, int fq) const {
;     ...
;                         float* op = outf + (size_t)r * DM + c0;
;                         const u32x4 xw = *(const u32x4*)(O + (size_t)r * DM + c0);
;                         float xf[8]; unpack8(xw, xf);
;                         const u32x4 pw = *(const u32x4*)(pe + (size_t)r * DM + c0);
;                         float pf[8]; unpack8(pw, pf);
;                         f32x4 o0, o1;
; #pragma unroll
;                         for (int j = 0; j < 4; ++j) { o0[j] = xf[j] + sigm(v[j]) * pf[j]; o1[j] = xf[4 + j] + sigm(v[4 + j]) * pf[4 + j]; }
;                         *(f32x4*)op = o0; *(f32x4*)(op + 4) = o1;
	v_add_f32_e32 v78, 1.0, v78
	v_add_f32_e32 v79, 1.0, v79
	v_rcp_f32_e32 v78, v78
	v_rcp_f32_e32 v79, v79
	v_mul_f32_e32 v68, 0xbfb8aa3b, v68
	v_mul_f32_e32 v64, 0xbfb8aa3b, v64
	v_mul_f32_e32 v69, 0xbfb8aa3b, v69
	v_mul_f32_e32 v65, 0xbfb8aa3b, v65
	v_mul_f32_e32 v70, 0xbfb8aa3b, v70
	v_mul_f32_e32 v71, 0xbfb8aa3b, v71
	v_mul_f32_e32 v66, 0xbfb8aa3b, v66
	v_mul_f32_e32 v67, 0xbfb8aa3b, v67
	v_exp_f32_e32 v68, v68
	v_exp_f32_e32 v69, v69
	v_exp_f32_e32 v70, v70
	v_exp_f32_e32 v71, v71
	v_mul_f32_e32 v60, 0xbfb8aa3b, v60
	v_mul_f32_e32 v56, 0xbfb8aa3b, v56
	v_add_f32_e32 v70, 1.0, v70
	v_add_f32_e32 v71, 1.0, v71
	v_rcp_f32_e32 v70, v70
	v_rcp_f32_e32 v71, v71
	v_mul_f32_e32 v61, 0xbfb8aa3b, v61
	v_mul_f32_e32 v57, 0xbfb8aa3b, v57
	v_mul_f32_e32 v62, 0xbfb8aa3b, v62
	v_mul_f32_e32 v63, 0xbfb8aa3b, v63
	v_mul_f32_e32 v58, 0xbfb8aa3b, v58
	v_mul_f32_e32 v59, 0xbfb8aa3b, v59
	v_exp_f32_e32 v60, v60
	v_exp_f32_e32 v61, v61
	v_exp_f32_e32 v62, v62
	v_exp_f32_e32 v63, v63
	v_exp_f32_e32 v58, v58
	v_exp_f32_e32 v59, v59
	v_add_f32_e32 v60, 1.0, v60
	v_add_f32_e32 v61, 1.0, v61
	v_add_f32_e32 v62, 1.0, v62
	v_add_f32_e32 v63, 1.0, v63
	v_rcp_f32_e32 v62, v62
	v_rcp_f32_e32 v63, v63
	v_mul_f32_e32 v52, 0xbfb8aa3b, v52
	v_mul_f32_e32 v48, 0xbfb8aa3b, v48
	v_mul_f32_e32 v53, 0xbfb8aa3b, v53
	v_mul_f32_e32 v49, 0xbfb8aa3b, v49
	v_mul_f32_e32 v54, 0xbfb8aa3b, v54
	v_mul_f32_e32 v55, 0xbfb8aa3b, v55
	v_mul_f32_e32 v50, 0xbfb8aa3b, v50
	v_mul_f32_e32 v51, 0xbfb8aa3b, v51
	v_exp_f32_e32 v52, v52
	v_exp_f32_e32 v53, v53
	v_exp_f32_e32 v54, v54
	v_exp_f32_e32 v55, v55
	v_mul_f32_e32 v44, 0xbfb8aa3b, v44
	v_mul_f32_e32 v40, 0xbfb8aa3b, v40
	v_add_f32_e32 v54, 1.0, v54
	v_add_f32_e32 v55, 1.0, v55
	v_rcp_f32_e32 v54, v54
	s_waitcnt vmcnt(18)
	v_mov_b64_e32 v[112:113], v[196:197]
	v_mov_b64_e32 v[114:115], v[198:199]
	v_mov_b64_e32 v[116:117], v[200:201]
	v_mov_b64_e32 v[118:119], v[202:203]
	v_lshlrev_b32_e32 v108, 16, v112
	v_and_b32_e32 v109, 0xffff0000, v112
	v_lshlrev_b32_e32 v154, 16, v116
	v_and_b32_e32 v155, 0xffff0000, v116
	v_lshlrev_b32_e32 v156, 16, v114
	v_and_b32_e32 v157, 0xffff0000, v114
	v_lshlrev_b32_e32 v158, 16, v118
	v_and_b32_e32 v159, 0xffff0000, v118
	v_lshlrev_b32_e32 v112, 16, v113
	v_and_b32_e32 v113, 0xffff0000, v113
	v_lshlrev_b32_e32 v116, 16, v117
	v_and_b32_e32 v117, 0xffff0000, v117
	v_lshlrev_b32_e32 v114, 16, v115
	v_and_b32_e32 v115, 0xffff0000, v115
	v_lshlrev_b32_e32 v118, 16, v119
	v_and_b32_e32 v119, 0xffff0000, v119
	v_pk_fma_f32 v[104:105], v[104:105], v[154:155], v[108:109]
	v_pk_fma_f32 v[108:109], v[106:107], v[158:159], v[156:157]
	v_pk_fma_f32 v[106:107], v[110:111], v[116:117], v[112:113]
	v_pk_fma_f32 v[110:111], v[126:127], v[118:119], v[114:115]
	global_store_dwordx4 v[124:125], v[104:107], off
	global_store_dwordx4 v[124:125], v[108:111], off offset:16
	global_load_dwordx4 v[196:199], v[244:245], off
	global_load_dwordx4 v[200:203], v[248:249], off
	v_exp_f32_e32 v116, v96
	v_exp_f32_e32 v117, v97
	v_exp_f32_e32 v118, v98
	v_exp_f32_e32 v119, v99
	v_or_b32_e32 v112, 32, v146
	v_ashrrev_i32_e32 v113, 31, v112
	v_lshlrev_b64 v[96:97], 11, v[112:113]
	v_lshl_add_u64 v[98:99], s[48:49], 0, v[96:97]
	v_lshl_add_u64 v[114:115], s[38:39], 0, v[96:97]
	v_add_f32_e32 v96, 1.0, v100
	v_add_f32_e32 v97, 1.0, v116
	v_add_f32_e32 v100, 1.0, v101
	v_add_f32_e32 v101, 1.0, v117
	v_add_f32_e32 v118, 1.0, v118
	v_add_f32_e32 v119, 1.0, v119
	v_lshl_add_u64 v[116:117], v[98:99], 0, v[144:145]
	v_rcp_f32_e32 v96, v96
	v_rcp_f32_e32 v98, v97
	v_rcp_f32_e32 v97, v100
	v_rcp_f32_e32 v99, v101
	v_rcp_f32_e32 v118, v118
	v_rcp_f32_e32 v119, v119
	v_rcp_f32_e32 v55, v55
	v_mul_f32_e32 v45, 0xbfb8aa3b, v45
	v_mul_f32_e32 v41, 0xbfb8aa3b, v41
	v_mul_f32_e32 v46, 0xbfb8aa3b, v46
	v_mul_f32_e32 v47, 0xbfb8aa3b, v47
	v_mul_f32_e32 v42, 0xbfb8aa3b, v42
	v_mul_f32_e32 v43, 0xbfb8aa3b, v43
	v_exp_f32_e32 v44, v44
	v_exp_f32_e32 v45, v45
	v_exp_f32_e32 v46, v46
	v_exp_f32_e32 v47, v47
	v_exp_f32_e32 v42, v42
	v_exp_f32_e32 v43, v43
	v_add_f32_e32 v44, 1.0, v44
	v_add_f32_e32 v45, 1.0, v45
	v_add_f32_e32 v46, 1.0, v46
	v_add_f32_e32 v47, 1.0, v47
	v_rcp_f32_e32 v46, v46
	v_rcp_f32_e32 v47, v47
	v_mul_f32_e32 v36, 0xbfb8aa3b, v36
	v_mul_f32_e32 v32, 0xbfb8aa3b, v32
	v_mul_f32_e32 v37, 0xbfb8aa3b, v37
	v_mul_f32_e32 v33, 0xbfb8aa3b, v33
	v_mul_f32_e32 v38, 0xbfb8aa3b, v38
	v_mul_f32_e32 v39, 0xbfb8aa3b, v39
	v_mul_f32_e32 v34, 0xbfb8aa3b, v34
	v_mul_f32_e32 v35, 0xbfb8aa3b, v35
	v_exp_f32_e32 v36, v36
	v_exp_f32_e32 v37, v37
	v_exp_f32_e32 v38, v38
	v_exp_f32_e32 v39, v39
	v_mul_f32_e32 v28, 0xbfb8aa3b, v28
	v_mul_f32_e32 v24, 0xbfb8aa3b, v24
	v_add_f32_e32 v38, 1.0, v38
	v_add_f32_e32 v39, 1.0, v39
	v_rcp_f32_e32 v38, v38
	v_rcp_f32_e32 v39, v39
	v_mul_f32_e32 v29, 0xbfb8aa3b, v29
	v_mul_f32_e32 v25, 0xbfb8aa3b, v25
	v_mul_f32_e32 v30, 0xbfb8aa3b, v30
	v_mul_f32_e32 v31, 0xbfb8aa3b, v31
	v_mul_f32_e32 v26, 0xbfb8aa3b, v26
	v_mul_f32_e32 v27, 0xbfb8aa3b, v27
	v_exp_f32_e32 v28, v28
	v_exp_f32_e32 v29, v29
	v_exp_f32_e32 v30, v30
	v_exp_f32_e32 v31, v31
	v_exp_f32_e32 v26, v26
	v_exp_f32_e32 v27, v27
	v_add_f32_e32 v28, 1.0, v28
	v_add_f32_e32 v29, 1.0, v29
	v_add_f32_e32 v30, 1.0, v30
	v_add_f32_e32 v31, 1.0, v31
	v_rcp_f32_e32 v30, v30
	v_rcp_f32_e32 v31, v31
	v_mul_f32_e32 v20, 0xbfb8aa3b, v20
	s_waitcnt vmcnt(20)
; __device__ __forceinline__ float bf_lo(unsigned w) { return __uint_as_float(w << 16); }
; __device__ __forceinline__ float bf_hi(unsigned w) { return __uint_as_float(w & 0xffff0000u); }
; __device__ __forceinline__ float sigm(float x) { return __builtin_amdgcn_rcpf(1.f + __expf(-x)); }
; __device__ __forceinline__ void unpack8(const u32x4 w, float (&f)[8]) {
;     f[0] = bf_lo(w.x); f[1] = bf_hi(w.x); f[2] = bf_lo(w.y); f[3] = bf_hi(w.y); f[4] = bf_lo(w.z); f[5] = bf_hi(w.z); f[6] = bf_lo(w.w); f[7] = bf_hi(w.w); }
;     __device__ __forceinline__ void operator()(const f32x4 (&acc)[2][2][4][2], const pg8::Unit& u, int wr, int wc, int fr, int fq) const {
;     ...
;                         float* op = outf + (size_t)r * DM + c0;
;                         const u32x4 xw = *(const u32x4*)(O + (size_t)r * DM + c0);
;                         float xf[8]; unpack8(xw, xf);
;                         const u32x4 pw = *(const u32x4*)(pe + (size_t)r * DM + c0);
;                         float pf[8]; unpack8(pw, pf);
;                         f32x4 o0, o1;
; #pragma unroll
;                         for (int j = 0; j < 4; ++j) { o0[j] = xf[j] + sigm(v[j]) * pf[j]; o1[j] = xf[4 + j] + sigm(v[4 + j]) * pf[4 + j]; }
;                         *(f32x4*)op = o0; *(f32x4*)(op + 4) = o1;
	v_mov_b64_e32 v[104:105], v[204:205]
	v_mov_b64_e32 v[106:107], v[206:207]
	v_mov_b64_e32 v[108:109], v[208:209]
	v_mov_b64_e32 v[110:111], v[210:211]
	v_lshlrev_b32_e32 v100, 16, v104
	v_and_b32_e32 v101, 0xffff0000, v104
	v_lshlrev_b32_e32 v122, 16, v108
	v_and_b32_e32 v123, 0xffff0000, v108
	v_lshlrev_b32_e32 v126, 16, v106
	v_and_b32_e32 v127, 0xffff0000, v106
	v_lshlrev_b32_e32 v154, 16, v110
	v_and_b32_e32 v155, 0xffff0000, v110
	v_lshlrev_b32_e32 v104, 16, v105
	v_and_b32_e32 v105, 0xffff0000, v105
	v_lshlrev_b32_e32 v108, 16, v109
	v_and_b32_e32 v109, 0xffff0000, v109
	v_lshlrev_b32_e32 v106, 16, v107
	v_and_b32_e32 v107, 0xffff0000, v107
	v_lshlrev_b32_e32 v110, 16, v111
	v_and_b32_e32 v111, 0xffff0000, v111
	v_pk_fma_f32 v[96:97], v[96:97], v[122:123], v[100:101]
	v_pk_fma_f32 v[100:101], v[98:99], v[154:155], v[126:127]
	v_pk_fma_f32 v[98:99], v[102:103], v[108:109], v[104:105]
	v_pk_fma_f32 v[102:103], v[118:119], v[110:111], v[106:107]
	global_store_dwordx4 v[124:125], v[96:99], off offset:512
	global_store_dwordx4 v[124:125], v[100:103], off offset:528
	global_load_dwordx4 v[204:207], v[244:245], off offset:256
	global_load_dwordx4 v[208:211], v[248:249], off offset:256
	v_lshl_add_u64 v[244:245], v[244:245], 0, s[60:61]
	v_lshl_add_u64 v[248:249], v[248:249], 0, s[60:61]
	v_lshl_add_u64 v[104:105], v[114:115], 0, v[144:145]
	v_exp_f32_e32 v106, v88
	v_exp_f32_e32 v107, v89
	v_lshlrev_b64 v[88:89], 12, v[112:113]
	v_lshl_add_u64 v[88:89], s[84:85], 0, v[88:89]
	v_add_f32_e32 v108, 1.0, v106
	v_add_f32_e32 v109, 1.0, v107
	v_add_f32_e32 v110, 1.0, v90
	v_add_f32_e32 v111, 1.0, v91
	v_lshl_add_u64 v[106:107], v[88:89], 0, v[120:121]
	v_rcp_f32_e32 v88, v92
	v_rcp_f32_e32 v90, v108
	v_rcp_f32_e32 v89, v93
	v_rcp_f32_e32 v91, v109
	v_rcp_f32_e32 v108, v110
	v_rcp_f32_e32 v109, v111
	v_mul_f32_e32 v16, 0xbfb8aa3b, v16
	v_mul_f32_e32 v21, 0xbfb8aa3b, v21
	v_mul_f32_e32 v17, 0xbfb8aa3b, v17
	v_mul_f32_e32 v22, 0xbfb8aa3b, v22
	v_mul_f32_e32 v23, 0xbfb8aa3b, v23
	v_mul_f32_e32 v18, 0xbfb8aa3b, v18
	v_mul_f32_e32 v19, 0xbfb8aa3b, v19
	v_exp_f32_e32 v20, v20
	v_exp_f32_e32 v21, v21
	v_exp_f32_e32 v22, v22
	v_exp_f32_e32 v23, v23
	v_mul_f32_e32 v12, 0xbfb8aa3b, v12
	v_mul_f32_e32 v8, 0xbfb8aa3b, v8
	v_add_f32_e32 v22, 1.0, v22
	v_add_f32_e32 v23, 1.0, v23
	v_rcp_f32_e32 v22, v22
	v_rcp_f32_e32 v23, v23
	v_mul_f32_e32 v13, 0xbfb8aa3b, v13
	v_mul_f32_e32 v9, 0xbfb8aa3b, v9
	v_mul_f32_e32 v14, 0xbfb8aa3b, v14
	v_mul_f32_e32 v15, 0xbfb8aa3b, v15
	v_mul_f32_e32 v10, 0xbfb8aa3b, v10
	v_mul_f32_e32 v11, 0xbfb8aa3b, v11
	v_exp_f32_e32 v12, v12
	v_exp_f32_e32 v13, v13
	v_exp_f32_e32 v14, v14
	v_exp_f32_e32 v15, v15
	v_exp_f32_e32 v10, v10
	v_exp_f32_e32 v11, v11
	v_add_f32_e32 v12, 1.0, v12
	v_add_f32_e32 v13, 1.0, v13
	v_add_f32_e32 v14, 1.0, v14
	v_add_f32_e32 v15, 1.0, v15
	v_rcp_f32_e32 v14, v14
	v_rcp_f32_e32 v15, v15
	v_mul_f32_e32 v4, 0xbfb8aa3b, v4
	v_mul_f32_e32 v0, 0xbfb8aa3b, v0
	v_mul_f32_e32 v5, 0xbfb8aa3b, v5
	v_mul_f32_e32 v1, 0xbfb8aa3b, v1
	v_mul_f32_e32 v6, 0xbfb8aa3b, v6
	v_mul_f32_e32 v7, 0xbfb8aa3b, v7
	v_mul_f32_e32 v2, 0xbfb8aa3b, v2
	v_mul_f32_e32 v3, 0xbfb8aa3b, v3
	v_exp_f32_e32 v4, v4
	v_exp_f32_e32 v0, v0
	v_exp_f32_e32 v5, v5
	v_exp_f32_e32 v1, v1
	v_exp_f32_e32 v6, v6
	v_exp_f32_e32 v7, v7
	v_exp_f32_e32 v2, v2
	v_exp_f32_e32 v3, v3
	v_add_f32_e32 v4, 1.0, v4
	v_add_f32_e32 v5, 1.0, v5
	v_add_f32_e32 v6, 1.0, v6
	v_add_f32_e32 v7, 1.0, v7
	v_rcp_f32_e32 v6, v6
	v_rcp_f32_e32 v7, v7
	s_andn2_b64 vcc, exec, s[0:1]
	s_mov_b64 s[0:1], -1
	s_waitcnt vmcnt(22)
	v_mov_b64_e32 v[96:97], v[212:213]
	v_mov_b64_e32 v[98:99], v[214:215]
	v_mov_b64_e32 v[100:101], v[216:217]
	v_mov_b64_e32 v[102:103], v[218:219]
	v_lshlrev_b32_e32 v92, 16, v96
	v_and_b32_e32 v93, 0xffff0000, v96
	v_lshlrev_b32_e32 v110, 16, v100
	v_and_b32_e32 v111, 0xffff0000, v100
	v_lshlrev_b32_e32 v112, 16, v98
	v_and_b32_e32 v113, 0xffff0000, v98
	v_lshlrev_b32_e32 v114, 16, v102
	v_and_b32_e32 v115, 0xffff0000, v102
	v_lshlrev_b32_e32 v96, 16, v97
	v_and_b32_e32 v97, 0xffff0000, v97
	v_lshlrev_b32_e32 v100, 16, v101
	v_and_b32_e32 v101, 0xffff0000, v101
	v_lshlrev_b32_e32 v98, 16, v99
	v_and_b32_e32 v99, 0xffff0000, v99
	v_lshlrev_b32_e32 v102, 16, v103
	v_and_b32_e32 v103, 0xffff0000, v103
	v_pk_fma_f32 v[88:89], v[88:89], v[110:111], v[92:93]
	v_pk_fma_f32 v[92:93], v[90:91], v[114:115], v[112:113]
	v_pk_fma_f32 v[90:91], v[94:95], v[100:101], v[96:97]
	v_pk_fma_f32 v[94:95], v[108:109], v[102:103], v[98:99]
	global_store_dwordx4 v[106:107], v[88:91], off
	global_store_dwordx4 v[106:107], v[92:95], off offset:16
	global_load_dwordx4 v[212:215], v[244:245], off
	global_load_dwordx4 v[216:219], v[248:249], off
	v_exp_f32_e32 v100, v80
	v_exp_f32_e32 v101, v81
	v_exp_f32_e32 v102, v82
	v_exp_f32_e32 v103, v83
	v_or_b32_e32 v96, 48, v146
	v_ashrrev_i32_e32 v97, 31, v96
	v_lshlrev_b64 v[80:81], 11, v[96:97]
	v_lshl_add_u64 v[82:83], s[48:49], 0, v[80:81]
	v_lshl_add_u64 v[98:99], s[38:39], 0, v[80:81]
	v_add_f32_e32 v80, 1.0, v84
	v_add_f32_e32 v81, 1.0, v100
	v_add_f32_e32 v84, 1.0, v85
	v_add_f32_e32 v85, 1.0, v101
	v_add_f32_e32 v102, 1.0, v102
	v_add_f32_e32 v103, 1.0, v103
	v_lshl_add_u64 v[100:101], v[82:83], 0, v[144:145]
	v_rcp_f32_e32 v80, v80
	v_rcp_f32_e32 v82, v81
	v_rcp_f32_e32 v81, v84
	v_rcp_f32_e32 v83, v85
	v_rcp_f32_e32 v102, v102
	v_rcp_f32_e32 v103, v103
	s_waitcnt vmcnt(24)
; __device__ __forceinline__ float bf_lo(unsigned w) { return __uint_as_float(w << 16); }
; __device__ __forceinline__ float bf_hi(unsigned w) { return __uint_as_float(w & 0xffff0000u); }
; __device__ __forceinline__ float sigm(float x) { return __builtin_amdgcn_rcpf(1.f + __expf(-x)); }
; __device__ __forceinline__ void unpack8(const u32x4 w, float (&f)[8]) {
;     f[0] = bf_lo(w.x); f[1] = bf_hi(w.x); f[2] = bf_lo(w.y); f[3] = bf_hi(w.y); f[4] = bf_lo(w.z); f[5] = bf_hi(w.z); f[6] = bf_lo(w.w); f[7] = bf_hi(w.w); }
;     __device__ __forceinline__ void operator()(const f32x4 (&acc)[2][2][4][2], const pg8::Unit& u, int wr, int wc, int fr, int fq) const {
;     ...
;                         float* op = outf + (size_t)r * DM + c0;
;                         const u32x4 xw = *(const u32x4*)(O + (size_t)r * DM + c0);
;                         float xf[8]; unpack8(xw, xf);
;                         const u32x4 pw = *(const u32x4*)(pe + (size_t)r * DM + c0);
;                         float pf[8]; unpack8(pw, pf);
;                         f32x4 o0, o1;
; #pragma unroll
;                         for (int j = 0; j < 4; ++j) { o0[j] = xf[j] + sigm(v[j]) * pf[j]; o1[j] = xf[4 + j] + sigm(v[4 + j]) * pf[4 + j]; }
;                         *(f32x4*)op = o0; *(f32x4*)(op + 4) = o1;
	v_mov_b64_e32 v[88:89], v[220:221]
	v_mov_b64_e32 v[90:91], v[222:223]
	v_mov_b64_e32 v[92:93], v[224:225]
	v_mov_b64_e32 v[94:95], v[226:227]
	v_lshlrev_b32_e32 v84, 16, v88
	v_and_b32_e32 v85, 0xffff0000, v88
	v_lshlrev_b32_e32 v104, 16, v92
	v_and_b32_e32 v105, 0xffff0000, v92
	v_lshlrev_b32_e32 v108, 16, v90
	v_and_b32_e32 v109, 0xffff0000, v90
	v_lshlrev_b32_e32 v110, 16, v94
	v_and_b32_e32 v111, 0xffff0000, v94
	v_lshlrev_b32_e32 v88, 16, v89
	v_and_b32_e32 v89, 0xffff0000, v89
	v_lshlrev_b32_e32 v92, 16, v93
	v_and_b32_e32 v93, 0xffff0000, v93
	v_lshlrev_b32_e32 v90, 16, v91
	v_and_b32_e32 v91, 0xffff0000, v91
	v_lshlrev_b32_e32 v94, 16, v95
	v_and_b32_e32 v95, 0xffff0000, v95
	v_pk_fma_f32 v[80:81], v[80:81], v[104:105], v[84:85]
	v_pk_fma_f32 v[84:85], v[82:83], v[110:111], v[108:109]
	v_pk_fma_f32 v[82:83], v[86:87], v[92:93], v[88:89]
	v_pk_fma_f32 v[86:87], v[102:103], v[94:95], v[90:91]
	global_store_dwordx4 v[106:107], v[80:83], off offset:512
	global_store_dwordx4 v[106:107], v[84:87], off offset:528
	global_load_dwordx4 v[220:223], v[244:245], off offset:256
	global_load_dwordx4 v[224:227], v[248:249], off offset:256
	v_lshl_add_u64 v[244:245], v[244:245], 0, s[60:61]
	v_lshl_add_u64 v[248:249], v[248:249], 0, s[60:61]
	v_lshl_add_u64 v[88:89], v[98:99], 0, v[144:145]
	v_exp_f32_e32 v90, v72
	v_exp_f32_e32 v91, v73
	v_lshlrev_b64 v[72:73], 12, v[96:97]
	v_lshl_add_u64 v[72:73], s[84:85], 0, v[72:73]
	v_add_f32_e32 v92, 1.0, v90
	v_add_f32_e32 v93, 1.0, v91
	v_add_f32_e32 v94, 1.0, v74
	v_add_f32_e32 v95, 1.0, v75
	v_lshl_add_u64 v[90:91], v[72:73], 0, v[120:121]
	v_rcp_f32_e32 v72, v76
	v_rcp_f32_e32 v74, v92
	v_rcp_f32_e32 v73, v77
	v_rcp_f32_e32 v75, v93
	v_rcp_f32_e32 v92, v94
	v_rcp_f32_e32 v93, v95
	s_waitcnt vmcnt(26)
	v_mov_b64_e32 v[80:81], v[228:229]
	v_mov_b64_e32 v[82:83], v[230:231]
	v_mov_b64_e32 v[84:85], v[232:233]
	v_mov_b64_e32 v[86:87], v[234:235]
	v_lshlrev_b32_e32 v76, 16, v80
	v_and_b32_e32 v77, 0xffff0000, v80
	v_lshlrev_b32_e32 v94, 16, v84
	v_and_b32_e32 v95, 0xffff0000, v84
	v_lshlrev_b32_e32 v96, 16, v82
	v_and_b32_e32 v97, 0xffff0000, v82
	v_lshlrev_b32_e32 v98, 16, v86
	v_and_b32_e32 v99, 0xffff0000, v86
	v_lshlrev_b32_e32 v80, 16, v81
	v_and_b32_e32 v81, 0xffff0000, v81
	v_lshlrev_b32_e32 v84, 16, v85
	v_and_b32_e32 v85, 0xffff0000, v85
	v_lshlrev_b32_e32 v82, 16, v83
	v_and_b32_e32 v83, 0xffff0000, v83
	v_lshlrev_b32_e32 v86, 16, v87
	v_and_b32_e32 v87, 0xffff0000, v87
	v_pk_fma_f32 v[72:73], v[72:73], v[94:95], v[76:77]
	v_pk_fma_f32 v[76:77], v[74:75], v[98:99], v[96:97]
	v_pk_fma_f32 v[74:75], v[78:79], v[84:85], v[80:81]
	v_pk_fma_f32 v[78:79], v[92:93], v[86:87], v[82:83]
	global_store_dwordx4 v[90:91], v[72:75], off
	global_store_dwordx4 v[90:91], v[76:79], off offset:16
	global_load_dwordx4 v[228:231], v[244:245], off
	global_load_dwordx4 v[232:235], v[248:249], off
	v_exp_f32_e32 v84, v64
	v_exp_f32_e32 v85, v65
	v_exp_f32_e32 v86, v66
	v_exp_f32_e32 v87, v67
	v_add_u32_e32 v80, 0x80, v146
	v_ashrrev_i32_e32 v81, 31, v80
	v_lshlrev_b64 v[64:65], 11, v[80:81]
	v_lshl_add_u64 v[66:67], s[48:49], 0, v[64:65]
	v_lshl_add_u64 v[82:83], s[38:39], 0, v[64:65]
	v_add_f32_e32 v64, 1.0, v68
	v_add_f32_e32 v65, 1.0, v84
	v_add_f32_e32 v68, 1.0, v69
	v_add_f32_e32 v69, 1.0, v85
	v_add_f32_e32 v86, 1.0, v86
	v_add_f32_e32 v87, 1.0, v87
	v_lshl_add_u64 v[84:85], v[66:67], 0, v[144:145]
	v_rcp_f32_e32 v64, v64
	v_rcp_f32_e32 v66, v65
	v_rcp_f32_e32 v65, v68
	v_rcp_f32_e32 v67, v69
	v_rcp_f32_e32 v86, v86
	v_rcp_f32_e32 v87, v87
	s_waitcnt vmcnt(28)
	v_mov_b64_e32 v[72:73], v[236:237]
	v_mov_b64_e32 v[74:75], v[238:239]
	v_mov_b64_e32 v[76:77], v[240:241]
	v_mov_b64_e32 v[78:79], v[242:243]
	v_lshlrev_b32_e32 v68, 16, v72
	v_and_b32_e32 v69, 0xffff0000, v72
	v_lshlrev_b32_e32 v88, 16, v76
	v_and_b32_e32 v89, 0xffff0000, v76
	v_lshlrev_b32_e32 v92, 16, v74
	v_and_b32_e32 v93, 0xffff0000, v74
	v_lshlrev_b32_e32 v94, 16, v78
	v_and_b32_e32 v95, 0xffff0000, v78
	v_lshlrev_b32_e32 v72, 16, v73
	v_and_b32_e32 v73, 0xffff0000, v73
	v_lshlrev_b32_e32 v76, 16, v77
	v_and_b32_e32 v77, 0xffff0000, v77
	v_lshlrev_b32_e32 v74, 16, v75
	v_and_b32_e32 v75, 0xffff0000, v75
	v_lshlrev_b32_e32 v78, 16, v79
	v_and_b32_e32 v79, 0xffff0000, v79
	v_pk_fma_f32 v[64:65], v[64:65], v[88:89], v[68:69]
	v_pk_fma_f32 v[68:69], v[66:67], v[94:95], v[92:93]
	v_pk_fma_f32 v[66:67], v[70:71], v[76:77], v[72:73]
	v_pk_fma_f32 v[70:71], v[86:87], v[78:79], v[74:75]
	global_store_dwordx4 v[90:91], v[64:67], off offset:512
	global_store_dwordx4 v[90:91], v[68:71], off offset:528
	global_load_dwordx4 v[236:239], v[244:245], off offset:256
	global_load_dwordx4 v[240:243], v[248:249], off offset:256
	v_lshl_add_u64 v[72:73], v[82:83], 0, v[144:145]
	v_exp_f32_e32 v74, v56
	v_exp_f32_e32 v75, v57
	v_lshlrev_b64 v[56:57], 12, v[80:81]
	v_lshl_add_u64 v[56:57], s[84:85], 0, v[56:57]
	v_add_f32_e32 v76, 1.0, v74
	v_add_f32_e32 v77, 1.0, v75
	v_add_f32_e32 v78, 1.0, v58
	v_add_f32_e32 v79, 1.0, v59
	v_lshl_add_u64 v[74:75], v[56:57], 0, v[120:121]
	v_rcp_f32_e32 v56, v60
	v_rcp_f32_e32 v58, v76
	v_rcp_f32_e32 v57, v61
	v_rcp_f32_e32 v59, v77
	v_rcp_f32_e32 v76, v78
	v_rcp_f32_e32 v77, v79
	s_waitcnt vmcnt(28)
; __device__ __forceinline__ float bf_lo(unsigned w) { return __uint_as_float(w << 16); }
; __device__ __forceinline__ float bf_hi(unsigned w) { return __uint_as_float(w & 0xffff0000u); }
; __device__ __forceinline__ float sigm(float x) { return __builtin_amdgcn_rcpf(1.f + __expf(-x)); }
; __device__ __forceinline__ void unpack8(const u32x4 w, float (&f)[8]) {
;     f[0] = bf_lo(w.x); f[1] = bf_hi(w.x); f[2] = bf_lo(w.y); f[3] = bf_hi(w.y); f[4] = bf_lo(w.z); f[5] = bf_hi(w.z); f[6] = bf_lo(w.w); f[7] = bf_hi(w.w); }
;     __device__ __forceinline__ void operator()(const f32x4 (&acc)[2][2][4][2], const pg8::Unit& u, int wr, int wc, int fr, int fq) const {
;     ...
;                         float* op = outf + (size_t)r * DM + c0;
;                         const u32x4 xw = *(const u32x4*)(O + (size_t)r * DM + c0);
;                         float xf[8]; unpack8(xw, xf);
;                         const u32x4 pw = *(const u32x4*)(pe + (size_t)r * DM + c0);
;                         float pf[8]; unpack8(pw, pf);
;                         f32x4 o0, o1;
; #pragma unroll
;                         for (int j = 0; j < 4; ++j) { o0[j] = xf[j] + sigm(v[j]) * pf[j]; o1[j] = xf[4 + j] + sigm(v[4 + j]) * pf[4 + j]; }
;                         *(f32x4*)op = o0; *(f32x4*)(op + 4) = o1;
	v_mov_b64_e32 v[64:65], v[180:181]
	v_mov_b64_e32 v[66:67], v[182:183]
	v_mov_b64_e32 v[68:69], v[184:185]
	v_mov_b64_e32 v[70:71], v[186:187]
	v_lshlrev_b32_e32 v60, 16, v64
	v_and_b32_e32 v61, 0xffff0000, v64
	v_lshlrev_b32_e32 v78, 16, v68
	v_and_b32_e32 v79, 0xffff0000, v68
	v_lshlrev_b32_e32 v80, 16, v66
	v_and_b32_e32 v81, 0xffff0000, v66
	v_lshlrev_b32_e32 v82, 16, v70
	v_and_b32_e32 v83, 0xffff0000, v70
	v_lshlrev_b32_e32 v64, 16, v65
	v_and_b32_e32 v65, 0xffff0000, v65
	v_lshlrev_b32_e32 v68, 16, v69
	v_and_b32_e32 v69, 0xffff0000, v69
	v_lshlrev_b32_e32 v66, 16, v67
	v_and_b32_e32 v67, 0xffff0000, v67
	v_lshlrev_b32_e32 v70, 16, v71
	v_and_b32_e32 v71, 0xffff0000, v71
	v_pk_fma_f32 v[56:57], v[56:57], v[78:79], v[60:61]
	v_pk_fma_f32 v[60:61], v[58:59], v[82:83], v[80:81]
	v_pk_fma_f32 v[58:59], v[62:63], v[68:69], v[64:65]
	v_pk_fma_f32 v[62:63], v[76:77], v[70:71], v[66:67]
	global_store_dwordx4 v[74:75], v[56:59], off
	global_store_dwordx4 v[74:75], v[60:63], off offset:16
	v_exp_f32_e32 v68, v48
	v_exp_f32_e32 v69, v49
	v_exp_f32_e32 v70, v50
	v_exp_f32_e32 v71, v51
	v_add_u32_e32 v64, 0x90, v146
	v_ashrrev_i32_e32 v65, 31, v64
	v_lshlrev_b64 v[48:49], 11, v[64:65]
	v_lshl_add_u64 v[50:51], s[48:49], 0, v[48:49]
	v_lshl_add_u64 v[66:67], s[38:39], 0, v[48:49]
	v_add_f32_e32 v48, 1.0, v52
	v_add_f32_e32 v49, 1.0, v68
	v_add_f32_e32 v52, 1.0, v53
	v_add_f32_e32 v53, 1.0, v69
	v_add_f32_e32 v70, 1.0, v70
	v_add_f32_e32 v71, 1.0, v71
	v_lshl_add_u64 v[68:69], v[50:51], 0, v[144:145]
	v_rcp_f32_e32 v48, v48
	v_rcp_f32_e32 v50, v49
	v_rcp_f32_e32 v49, v52
	v_rcp_f32_e32 v51, v53
	v_rcp_f32_e32 v70, v70
	v_rcp_f32_e32 v71, v71
	s_waitcnt vmcnt(26)
	v_mov_b64_e32 v[56:57], v[188:189]
	v_mov_b64_e32 v[58:59], v[190:191]
	v_mov_b64_e32 v[60:61], v[192:193]
	v_mov_b64_e32 v[62:63], v[194:195]
	v_lshlrev_b32_e32 v52, 16, v56
	v_and_b32_e32 v53, 0xffff0000, v56
	v_lshlrev_b32_e32 v72, 16, v60
	v_and_b32_e32 v73, 0xffff0000, v60
	v_lshlrev_b32_e32 v76, 16, v58
	v_and_b32_e32 v77, 0xffff0000, v58
	v_lshlrev_b32_e32 v78, 16, v62
	v_and_b32_e32 v79, 0xffff0000, v62
	v_lshlrev_b32_e32 v56, 16, v57
	v_and_b32_e32 v57, 0xffff0000, v57
	v_lshlrev_b32_e32 v60, 16, v61
	v_and_b32_e32 v61, 0xffff0000, v61
	v_lshlrev_b32_e32 v58, 16, v59
	v_and_b32_e32 v59, 0xffff0000, v59
	v_lshlrev_b32_e32 v62, 16, v63
	v_and_b32_e32 v63, 0xffff0000, v63
	v_pk_fma_f32 v[48:49], v[48:49], v[72:73], v[52:53]
	v_pk_fma_f32 v[52:53], v[50:51], v[78:79], v[76:77]
	v_pk_fma_f32 v[50:51], v[54:55], v[60:61], v[56:57]
	v_pk_fma_f32 v[54:55], v[70:71], v[62:63], v[58:59]
	global_store_dwordx4 v[74:75], v[48:51], off offset:512
	global_store_dwordx4 v[74:75], v[52:55], off offset:528
	v_lshl_add_u64 v[56:57], v[66:67], 0, v[144:145]
	v_exp_f32_e32 v58, v40
	v_exp_f32_e32 v59, v41
	v_lshlrev_b64 v[40:41], 12, v[64:65]
	v_lshl_add_u64 v[40:41], s[84:85], 0, v[40:41]
	v_add_f32_e32 v60, 1.0, v58
	v_add_f32_e32 v61, 1.0, v59
	v_add_f32_e32 v62, 1.0, v42
	v_add_f32_e32 v63, 1.0, v43
	v_lshl_add_u64 v[58:59], v[40:41], 0, v[120:121]
	v_rcp_f32_e32 v40, v44
	v_rcp_f32_e32 v42, v60
	v_rcp_f32_e32 v41, v45
	v_rcp_f32_e32 v43, v61
	v_rcp_f32_e32 v60, v62
	v_rcp_f32_e32 v61, v63
	s_waitcnt vmcnt(24)
	v_mov_b64_e32 v[48:49], v[196:197]
	v_mov_b64_e32 v[50:51], v[198:199]
	v_mov_b64_e32 v[52:53], v[200:201]
	v_mov_b64_e32 v[54:55], v[202:203]
	v_lshlrev_b32_e32 v44, 16, v48
	v_and_b32_e32 v45, 0xffff0000, v48
	v_lshlrev_b32_e32 v62, 16, v52
	v_and_b32_e32 v63, 0xffff0000, v52
	v_lshlrev_b32_e32 v64, 16, v50
	v_and_b32_e32 v65, 0xffff0000, v50
	v_lshlrev_b32_e32 v66, 16, v54
	v_and_b32_e32 v67, 0xffff0000, v54
	v_lshlrev_b32_e32 v48, 16, v49
	v_and_b32_e32 v49, 0xffff0000, v49
	v_lshlrev_b32_e32 v52, 16, v53
	v_and_b32_e32 v53, 0xffff0000, v53
	v_lshlrev_b32_e32 v50, 16, v51
	v_and_b32_e32 v51, 0xffff0000, v51
	v_lshlrev_b32_e32 v54, 16, v55
	v_and_b32_e32 v55, 0xffff0000, v55
	v_pk_fma_f32 v[40:41], v[40:41], v[62:63], v[44:45]
	v_pk_fma_f32 v[44:45], v[42:43], v[66:67], v[64:65]
	v_pk_fma_f32 v[42:43], v[46:47], v[52:53], v[48:49]
	v_pk_fma_f32 v[46:47], v[60:61], v[54:55], v[50:51]
	global_store_dwordx4 v[58:59], v[40:43], off
	global_store_dwordx4 v[58:59], v[44:47], off offset:16
	v_exp_f32_e32 v52, v32
	v_exp_f32_e32 v53, v33
	v_exp_f32_e32 v54, v34
	v_exp_f32_e32 v55, v35
	v_add_u32_e32 v48, 0xa0, v146
	v_ashrrev_i32_e32 v49, 31, v48
	v_lshlrev_b64 v[32:33], 11, v[48:49]
	v_lshl_add_u64 v[34:35], s[48:49], 0, v[32:33]
	v_lshl_add_u64 v[50:51], s[38:39], 0, v[32:33]
	v_add_f32_e32 v32, 1.0, v36
	v_add_f32_e32 v33, 1.0, v52
	v_add_f32_e32 v36, 1.0, v37
	v_add_f32_e32 v37, 1.0, v53
	v_add_f32_e32 v54, 1.0, v54
	v_add_f32_e32 v55, 1.0, v55
	v_lshl_add_u64 v[52:53], v[34:35], 0, v[144:145]
	v_rcp_f32_e32 v32, v32
	v_rcp_f32_e32 v34, v33
	v_rcp_f32_e32 v33, v36
	v_rcp_f32_e32 v35, v37
	v_rcp_f32_e32 v54, v54
	v_rcp_f32_e32 v55, v55
	s_waitcnt vmcnt(22)
; __device__ __forceinline__ float bf_lo(unsigned w) { return __uint_as_float(w << 16); }
; __device__ __forceinline__ float bf_hi(unsigned w) { return __uint_as_float(w & 0xffff0000u); }
; __device__ __forceinline__ float sigm(float x) { return __builtin_amdgcn_rcpf(1.f + __expf(-x)); }
; __device__ __forceinline__ void unpack8(const u32x4 w, float (&f)[8]) {
;     f[0] = bf_lo(w.x); f[1] = bf_hi(w.x); f[2] = bf_lo(w.y); f[3] = bf_hi(w.y); f[4] = bf_lo(w.z); f[5] = bf_hi(w.z); f[6] = bf_lo(w.w); f[7] = bf_hi(w.w); }
;     __device__ __forceinline__ void operator()(const f32x4 (&acc)[2][2][4][2], const pg8::Unit& u, int wr, int wc, int fr, int fq) const {
;     ...
;                         float* op = outf + (size_t)r * DM + c0;
;                         const u32x4 xw = *(const u32x4*)(O + (size_t)r * DM + c0);
;                         float xf[8]; unpack8(xw, xf);
;                         const u32x4 pw = *(const u32x4*)(pe + (size_t)r * DM + c0);
;                         float pf[8]; unpack8(pw, pf);
;                         f32x4 o0, o1;
; #pragma unroll
;                         for (int j = 0; j < 4; ++j) { o0[j] = xf[j] + sigm(v[j]) * pf[j]; o1[j] = xf[4 + j] + sigm(v[4 + j]) * pf[4 + j]; }
;                         *(f32x4*)op = o0; *(f32x4*)(op + 4) = o1;
	v_mov_b64_e32 v[40:41], v[204:205]
	v_mov_b64_e32 v[42:43], v[206:207]
	v_mov_b64_e32 v[44:45], v[208:209]
	v_mov_b64_e32 v[46:47], v[210:211]
	v_lshlrev_b32_e32 v36, 16, v40
	v_and_b32_e32 v37, 0xffff0000, v40
	v_lshlrev_b32_e32 v56, 16, v44
	v_and_b32_e32 v57, 0xffff0000, v44
	v_lshlrev_b32_e32 v60, 16, v42
	v_and_b32_e32 v61, 0xffff0000, v42
	v_lshlrev_b32_e32 v62, 16, v46
	v_and_b32_e32 v63, 0xffff0000, v46
	v_lshlrev_b32_e32 v40, 16, v41
	v_and_b32_e32 v41, 0xffff0000, v41
	v_lshlrev_b32_e32 v44, 16, v45
	v_and_b32_e32 v45, 0xffff0000, v45
	v_lshlrev_b32_e32 v42, 16, v43
	v_and_b32_e32 v43, 0xffff0000, v43
	v_lshlrev_b32_e32 v46, 16, v47
	v_and_b32_e32 v47, 0xffff0000, v47
	v_pk_fma_f32 v[32:33], v[32:33], v[56:57], v[36:37]
	v_pk_fma_f32 v[36:37], v[34:35], v[62:63], v[60:61]
	v_pk_fma_f32 v[34:35], v[38:39], v[44:45], v[40:41]
	v_pk_fma_f32 v[38:39], v[54:55], v[46:47], v[42:43]
	global_store_dwordx4 v[58:59], v[32:35], off offset:512
	global_store_dwordx4 v[58:59], v[36:39], off offset:528
	v_lshl_add_u64 v[40:41], v[50:51], 0, v[144:145]
	v_exp_f32_e32 v42, v24
	v_exp_f32_e32 v43, v25
	v_lshlrev_b64 v[24:25], 12, v[48:49]
	v_lshl_add_u64 v[24:25], s[84:85], 0, v[24:25]
	v_add_f32_e32 v44, 1.0, v42
	v_add_f32_e32 v45, 1.0, v43
	v_add_f32_e32 v46, 1.0, v26
	v_add_f32_e32 v47, 1.0, v27
	v_lshl_add_u64 v[42:43], v[24:25], 0, v[120:121]
	v_rcp_f32_e32 v24, v28
	v_rcp_f32_e32 v26, v44
	v_rcp_f32_e32 v25, v29
	v_rcp_f32_e32 v27, v45
	v_rcp_f32_e32 v44, v46
	v_rcp_f32_e32 v45, v47
	s_waitcnt vmcnt(20)
	v_mov_b64_e32 v[32:33], v[212:213]
	v_mov_b64_e32 v[34:35], v[214:215]
	v_mov_b64_e32 v[36:37], v[216:217]
	v_mov_b64_e32 v[38:39], v[218:219]
	v_lshlrev_b32_e32 v28, 16, v32
	v_and_b32_e32 v29, 0xffff0000, v32
	v_lshlrev_b32_e32 v46, 16, v36
	v_and_b32_e32 v47, 0xffff0000, v36
	v_lshlrev_b32_e32 v48, 16, v34
	v_and_b32_e32 v49, 0xffff0000, v34
	v_lshlrev_b32_e32 v50, 16, v38
	v_and_b32_e32 v51, 0xffff0000, v38
	v_lshlrev_b32_e32 v32, 16, v33
	v_and_b32_e32 v33, 0xffff0000, v33
	v_lshlrev_b32_e32 v36, 16, v37
	v_and_b32_e32 v37, 0xffff0000, v37
	v_lshlrev_b32_e32 v34, 16, v35
	v_and_b32_e32 v35, 0xffff0000, v35
	v_lshlrev_b32_e32 v38, 16, v39
	v_and_b32_e32 v39, 0xffff0000, v39
	v_pk_fma_f32 v[24:25], v[24:25], v[46:47], v[28:29]
	v_pk_fma_f32 v[28:29], v[26:27], v[50:51], v[48:49]
	v_pk_fma_f32 v[26:27], v[30:31], v[36:37], v[32:33]
	v_pk_fma_f32 v[30:31], v[44:45], v[38:39], v[34:35]
	global_store_dwordx4 v[42:43], v[24:27], off
	global_store_dwordx4 v[42:43], v[28:31], off offset:16
	v_exp_f32_e32 v36, v16
	v_exp_f32_e32 v37, v17
	v_exp_f32_e32 v38, v18
	v_exp_f32_e32 v39, v19
	v_add_u32_e32 v32, 0xb0, v146
	v_ashrrev_i32_e32 v33, 31, v32
	v_lshlrev_b64 v[16:17], 11, v[32:33]
	v_lshl_add_u64 v[18:19], s[48:49], 0, v[16:17]
	v_lshl_add_u64 v[34:35], s[38:39], 0, v[16:17]
	v_add_f32_e32 v16, 1.0, v20
	v_add_f32_e32 v17, 1.0, v36
	v_add_f32_e32 v20, 1.0, v21
	v_add_f32_e32 v21, 1.0, v37
	v_add_f32_e32 v38, 1.0, v38
	v_add_f32_e32 v39, 1.0, v39
	v_lshl_add_u64 v[36:37], v[18:19], 0, v[144:145]
	v_rcp_f32_e32 v16, v16
	v_rcp_f32_e32 v18, v17
	v_rcp_f32_e32 v17, v20
	v_rcp_f32_e32 v19, v21
	v_rcp_f32_e32 v38, v38
	v_rcp_f32_e32 v39, v39
	s_waitcnt vmcnt(18)
	v_mov_b64_e32 v[24:25], v[220:221]
	v_mov_b64_e32 v[26:27], v[222:223]
	v_mov_b64_e32 v[28:29], v[224:225]
	v_mov_b64_e32 v[30:31], v[226:227]
	v_lshlrev_b32_e32 v20, 16, v24
	v_and_b32_e32 v21, 0xffff0000, v24
	v_lshlrev_b32_e32 v40, 16, v28
	v_and_b32_e32 v41, 0xffff0000, v28
	v_lshlrev_b32_e32 v44, 16, v26
	v_and_b32_e32 v45, 0xffff0000, v26
	v_lshlrev_b32_e32 v46, 16, v30
	v_and_b32_e32 v47, 0xffff0000, v30
	v_lshlrev_b32_e32 v24, 16, v25
	v_and_b32_e32 v25, 0xffff0000, v25
	v_lshlrev_b32_e32 v28, 16, v29
	v_and_b32_e32 v29, 0xffff0000, v29
	v_lshlrev_b32_e32 v26, 16, v27
	v_and_b32_e32 v27, 0xffff0000, v27
	v_lshlrev_b32_e32 v30, 16, v31
	v_and_b32_e32 v31, 0xffff0000, v31
	v_pk_fma_f32 v[16:17], v[16:17], v[40:41], v[20:21]
	v_pk_fma_f32 v[20:21], v[18:19], v[46:47], v[44:45]
	v_pk_fma_f32 v[18:19], v[22:23], v[28:29], v[24:25]
	v_pk_fma_f32 v[22:23], v[38:39], v[30:31], v[26:27]
	global_store_dwordx4 v[42:43], v[16:19], off offset:512
	global_store_dwordx4 v[42:43], v[20:23], off offset:528
	v_lshl_add_u64 v[24:25], v[34:35], 0, v[144:145]
	v_exp_f32_e32 v26, v8
	v_exp_f32_e32 v27, v9
	v_lshlrev_b64 v[8:9], 12, v[32:33]
	v_lshl_add_u64 v[8:9], s[84:85], 0, v[8:9]
	v_add_f32_e32 v28, 1.0, v26
	v_add_f32_e32 v29, 1.0, v27
	v_add_f32_e32 v30, 1.0, v10
	v_add_f32_e32 v31, 1.0, v11
	v_lshl_add_u64 v[26:27], v[8:9], 0, v[120:121]
	v_rcp_f32_e32 v8, v12
	v_rcp_f32_e32 v10, v28
	v_rcp_f32_e32 v9, v13
	v_rcp_f32_e32 v11, v29
	v_rcp_f32_e32 v28, v30
	v_rcp_f32_e32 v29, v31
	s_waitcnt vmcnt(16)
	v_mov_b64_e32 v[16:17], v[228:229]
	v_mov_b64_e32 v[18:19], v[230:231]
	v_mov_b64_e32 v[20:21], v[232:233]
	v_mov_b64_e32 v[22:23], v[234:235]
	v_lshlrev_b32_e32 v12, 16, v16
	v_and_b32_e32 v13, 0xffff0000, v16
	v_lshlrev_b32_e32 v30, 16, v20
	v_and_b32_e32 v31, 0xffff0000, v20
	v_lshlrev_b32_e32 v32, 16, v18
	v_and_b32_e32 v33, 0xffff0000, v18
	v_lshlrev_b32_e32 v34, 16, v22
	v_and_b32_e32 v35, 0xffff0000, v22
	v_lshlrev_b32_e32 v16, 16, v17
	v_and_b32_e32 v17, 0xffff0000, v17
	v_lshlrev_b32_e32 v20, 16, v21
	v_and_b32_e32 v21, 0xffff0000, v21
	v_lshlrev_b32_e32 v18, 16, v19
	v_and_b32_e32 v19, 0xffff0000, v19
	v_lshlrev_b32_e32 v22, 16, v23
	v_and_b32_e32 v23, 0xffff0000, v23
	v_pk_fma_f32 v[8:9], v[8:9], v[30:31], v[12:13]
	v_pk_fma_f32 v[12:13], v[10:11], v[34:35], v[32:33]
	v_pk_fma_f32 v[10:11], v[14:15], v[20:21], v[16:17]
	v_pk_fma_f32 v[14:15], v[28:29], v[22:23], v[18:19]
	global_store_dwordx4 v[26:27], v[8:11], off
	global_store_dwordx4 v[26:27], v[12:15], off offset:16
	v_add_f32_e32 v16, 1.0, v0
	v_add_f32_e32 v17, 1.0, v1
	v_add_f32_e32 v18, 1.0, v2
	v_add_f32_e32 v19, 1.0, v3
	v_rcp_f32_e32 v0, v4
	v_rcp_f32_e32 v2, v16
	v_rcp_f32_e32 v1, v5
	v_rcp_f32_e32 v3, v17
	v_rcp_f32_e32 v16, v18
	v_rcp_f32_e32 v17, v19
	s_waitcnt vmcnt(14)
	v_mov_b64_e32 v[8:9], v[236:237]
	v_mov_b64_e32 v[10:11], v[238:239]
	v_mov_b64_e32 v[12:13], v[240:241]
	v_mov_b64_e32 v[14:15], v[242:243]
	v_lshlrev_b32_e32 v4, 16, v8
	v_and_b32_e32 v5, 0xffff0000, v8
	v_lshlrev_b32_e32 v18, 16, v12
	v_and_b32_e32 v19, 0xffff0000, v12
	v_lshlrev_b32_e32 v20, 16, v10
	v_and_b32_e32 v21, 0xffff0000, v10
	v_lshlrev_b32_e32 v22, 16, v14
	v_and_b32_e32 v23, 0xffff0000, v14
	v_lshlrev_b32_e32 v8, 16, v9
	v_and_b32_e32 v9, 0xffff0000, v9
	v_lshlrev_b32_e32 v12, 16, v13
	v_and_b32_e32 v13, 0xffff0000, v13
	v_lshlrev_b32_e32 v10, 16, v11
	v_and_b32_e32 v11, 0xffff0000, v11
	v_lshlrev_b32_e32 v14, 16, v15
	v_and_b32_e32 v15, 0xffff0000, v15
	v_pk_fma_f32 v[0:1], v[0:1], v[18:19], v[4:5]
	v_pk_fma_f32 v[4:5], v[2:3], v[22:23], v[20:21]
	v_pk_fma_f32 v[2:3], v[6:7], v[12:13], v[8:9]
	v_pk_fma_f32 v[6:7], v[16:17], v[14:15], v[10:11]
	global_store_dwordx4 v[26:27], v[0:3], off offset:512
	global_store_dwordx4 v[26:27], v[4:7], off offset:528
	s_cbranch_vccnz .LBB0_1901
; #define PG8_BAR __builtin_amdgcn_s_barrier()
; template <class Epi, class Sched, bool ALIGN_EPI = true, bool SP2 = true>
; __device__ __forceinline__ void gemm_phase(LAS unsigned char* lds, const Gemm g, const Sched& S, const Epi& E) {
;     ...
;         if (!has_next) break;
; #pragma unroll
;         for (int a = 0; a < 2; ++a)
; #pragma unroll
;             for (int b = 0; b < 2; ++b)
; #pragma unroll
;                 for (int m = 0; m < 4; ++m)
; #pragma unroll
;                     for (int n = 0; n < 2; ++n) acc[a][b][m][n] = (f32x4){0.f, 0.f, 0.f, 0.f};
;         cur = nxt; cA = nA; cB = nB; ++ui;
;         if constexpr (ALIGN_EPI) { if (wr == 1) PG8_BAR; }
	s_andn2_b64 vcc, exec, s[4:5]
	s_cbranch_vccnz .LBB0_1900
	s_barrier
	s_branch .LBB0_1900
